# FFN-down residual epilogue: second-half d1 load issued with the first group, second vmcnt(0) per row dropped (plus attention loop variants)
# speedup vs baseline: 1.0075x; 1.0062x over previous
; __device__ __forceinline__ float bflo(unsigned w) { return __uint_as_float(w << 16); }
;     __device__ __forceinline__ void operator()(const pg8::f32x4 (&acc)[2][2][4][2], const pg8::Unit& u, int wr, int wc, int fr, int fq) const {
;     ...
;         for (int it = 0; it < 8; ++it) {
;             const int ai = it >> 2, m = it & 3;
;             const int rl = ai * 128 + wr * 64 + m * 16 + fr;
;             const size_t off = (size_t)(prow0 + rl) * DM + col0;
;             f32x4 cur[2][2];
; #pragma unroll
;             for (int bj = 0; bj < 2; ++bj) { cur[bj][0] = *(const f32x4*)(xin + off + bj * 128); cur[bj][1] = *(const f32x4*)(xin + off + bj * 128 + 4); }
;             float ss = 0.f;
; #pragma unroll
;             for (int bj = 0; bj < 2; ++bj) {
;                 f32x4 dl0 = gv[bj][0] * acc[ai][bj][m][0], dl1 = gv[bj][1] * acc[ai][bj][m][1];
;                 bf16* dp = d1 + (size_t)(u.pm * 256 + rl) * DM + col0 + bj * 128;
;                 if (dmode == 2) {
;                     const u32x4 dw = *(const u32x4*)dp;
;                     dl0 += (f32x4){bflo(dw[0]), bfhi(dw[0]), bflo(dw[1]), bfhi(dw[1])}; dl1 += (f32x4){bflo(dw[2]), bfhi(dw[2]), bflo(dw[3]), bfhi(dw[3])};
;                 }
;                 const f32x4 x0 = cur[bj][0] + dl0, x1 = cur[bj][1] + dl1;
;                 if (dmode == 1) { u32x4 dw; dw.x = cvt_pk_bf16(dl0[0], dl0[1]); dw.y = cvt_pk_bf16(dl0[2], dl0[3]); dw.z = cvt_pk_bf16(dl1[0], dl1[1]); dw.w = cvt_pk_bf16(dl1[2], dl1[3]); *(u32x4*)dp = dw; }
;                 else { *(f32x4*)(xout + off + bj * 128) = x0; *(f32x4*)(xout + off + bj * 128 + 4) = x1; }
;                 if (has_next) {
;                     ss += (x0[0] * x0[0] + x0[1] * x0[1]) + (x0[2] * x0[2] + x0[3] * x0[3]) + (x1[0] * x1[0] + x1[1] * x1[1]) + (x1[2] * x1[2] + x1[3] * x1[3]);
;                     const f32x4 y0 = x0 * gm[bj][0], y1 = x1 * gm[bj][1];
;                     u32x4 w; w.x = cvt_pk_bf16(y0[0], y0[1]); w.y = cvt_pk_bf16(y0[2], y0[3]); w.z = cvt_pk_bf16(y1[0], y1[1]); w.w = cvt_pk_bf16(y1[2], y1[3]);
;                     *(u32x4*)(xb + (size_t)(u.pm * 256 + rl) * DM + col0 + bj * 128) = w;
;                 }
;             }
;             if (has_next) {
;                 ss += __shfl_xor(ss, 16); ss += __shfl_xor(ss, 32);
;                 if (fq == 0) atomicAdd(rowss_next + u.pm * 256 + rl, ss);
;             }
;         }
.LBB0_727:
	s_lshl_b32 s34, s18, 8
	s_add_i32 s6, s34, 0xffff0000
	s_and_b64 s[4:5], exec, s[4:5]
	s_cselect_b32 s6, s6, s34
	v_add_u32_e32 v148, s6, v162
	v_ashrrev_i32_e32 v149, 31, v148
	v_add_u32_e32 v202, s34, v162
	v_readlane_b32 s4, v254, 47
	v_lshlrev_b64 v[148:149], 10, v[148:149]
	v_ashrrev_i32_e32 v203, 31, v202
	s_cselect_b32 s75, s4, s27
	v_readlane_b32 s4, v254, 48
	v_lshl_add_u64 v[148:149], v[148:149], 0, v[192:193]
	v_lshlrev_b64 v[204:205], 11, v[202:203]
	s_cselect_b32 s74, s4, s29
	v_lshlrev_b64 v[200:201], 2, v[148:149]
	v_lshl_add_u64 v[202:203], s[78:79], 0, v[204:205]
	v_lshl_add_u64 v[152:153], s[74:75], 0, v[200:201]
	v_lshl_add_u64 v[202:203], v[192:193], 1, v[202:203]
	global_load_dwordx4 v[226:229], v[152:153], off offset:16
	global_load_dwordx4 v[230:233], v[152:153], off
	global_load_dwordx4 v[148:151], v[152:153], off offset:528
	s_nop 0
	global_load_dwordx4 v[152:155], v[152:153], off offset:512
	s_cselect_b32 s59, s26, s67
	global_load_dwordx4 v[234:237], v[202:203], off
	global_load_dwordx4 v[240:243], v[202:203], off offset:256
	s_cselect_b32 s58, s25, s66
	v_lshl_add_u64 v[204:205], s[86:87], 0, v[204:205]
	v_lshl_add_u64 v[200:201], s[58:59], 0, v[200:201]
	s_and_b64 vcc, exec, s[40:41]
	v_lshl_add_u64 v[204:205], v[192:193], 1, v[204:205]
	s_waitcnt vmcnt(0)
	v_lshlrev_b32_e32 v216, 16, v234
	v_and_b32_e32 v217, 0xffff0000, v234
	v_lshlrev_b32_e32 v224, 16, v235
	v_and_b32_e32 v225, 0xffff0000, v235
	v_pk_fma_f32 v[144:145], v[144:145], v[44:45], v[216:217]
	v_pk_fma_f32 v[146:147], v[146:147], v[46:47], v[224:225]
	v_lshlrev_b32_e32 v216, 16, v236
	v_and_b32_e32 v217, 0xffff0000, v236
	v_lshlrev_b32_e32 v224, 16, v237
	v_and_b32_e32 v225, 0xffff0000, v237
	v_pk_fma_f32 v[140:141], v[140:141], v[48:49], v[216:217]
	v_pk_fma_f32 v[142:143], v[142:143], v[50:51], v[224:225]
	v_pk_add_f32 v[146:147], v[232:233], v[146:147]
	v_pk_add_f32 v[144:145], v[230:231], v[144:145]
	v_pk_add_f32 v[142:143], v[228:229], v[142:143]
	v_pk_add_f32 v[140:141], v[226:227], v[140:141]
	v_mov_b32_e32 v216, 0
	global_store_dwordx4 v[200:201], v[144:147], off
	global_store_dwordx4 v[200:201], v[140:143], off offset:16
	s_cbranch_vccnz .LBB0_729
	v_pk_mul_f32 v[216:217], v[146:147], v[146:147]
	v_pk_mul_f32 v[224:225], v[144:145], v[144:145]
	v_pk_mul_f32 v[146:147], v[196:197], v[146:147]
	v_pk_mov_b32 v[226:227], v[224:225], v[216:217] op_sel:[1,0]
	v_mov_b32_e32 v225, v217
	v_pk_add_f32 v[216:217], v[226:227], v[224:225]
	v_pk_mul_f32 v[224:225], v[142:143], v[142:143]
	v_pk_mul_f32 v[226:227], v[140:141], v[140:141]
	v_mov_b32_e32 v228, v224
	v_mov_b32_e32 v229, v226
	v_mov_b32_e32 v226, v225
	v_pk_add_f32 v[224:225], v[228:229], v[226:227]
	v_add_f32_e32 v216, v216, v217
	v_add_f32_e32 v216, v225, v216
	v_add_f32_e32 v216, v224, v216
	v_pk_mul_f32 v[144:145], v[194:195], v[144:145]
	v_pk_mul_f32 v[224:225], v[198:199], v[142:143]
	v_pk_mul_f32 v[142:143], v[190:191], v[140:141]
	v_cvt_pk_bf16_f32 v140, v144, v145
	v_cvt_pk_bf16_f32 v141, v146, v147
	v_cvt_pk_bf16_f32 v142, v142, v143
	v_cvt_pk_bf16_f32 v143, v224, v225
	global_store_dwordx4 v[204:205], v[140:143], off
.LBB0_729:
	s_ashr_i32 s35, s34, 31
	s_and_b64 vcc, exec, s[40:41]
	s_nop 1
	v_mov_b64_e32 v[140:141], v[240:241]
	v_mov_b64_e32 v[142:143], v[242:243]
	v_lshlrev_b32_e32 v144, 16, v140
	v_and_b32_e32 v145, 0xffff0000, v140
	v_lshlrev_b32_e32 v140, 16, v141
	v_and_b32_e32 v141, 0xffff0000, v141
	v_pk_fma_f32 v[138:139], v[138:139], v[30:31], v[140:141]
	v_lshlrev_b32_e32 v140, 16, v142
	v_and_b32_e32 v141, 0xffff0000, v142
	v_lshlrev_b32_e32 v142, 16, v143
	v_and_b32_e32 v143, 0xffff0000, v143
	v_pk_fma_f32 v[136:137], v[136:137], v[28:29], v[144:145]
	v_pk_fma_f32 v[132:133], v[132:133], v[40:41], v[140:141]
	v_pk_fma_f32 v[134:135], v[134:135], v[42:43], v[142:143]
	v_pk_add_f32 v[138:139], v[154:155], v[138:139]
	v_pk_add_f32 v[136:137], v[152:153], v[136:137]
	v_pk_add_f32 v[134:135], v[150:151], v[134:135]
	v_pk_add_f32 v[132:133], v[148:149], v[132:133]
	global_store_dwordx4 v[200:201], v[136:139], off offset:512
	global_store_dwordx4 v[200:201], v[132:135], off offset:528
	s_cbranch_vccnz .LBB0_733
	v_pk_mul_f32 v[140:141], v[188:189], v[138:139]
	v_mul_f32_e32 v144, v137, v137
	v_mul_f32_e32 v139, v139, v139
	v_mul_f32_e32 v143, v133, v133
	v_fmac_f32_e32 v144, v136, v136
	v_fmac_f32_e32 v139, v138, v138
	v_mul_f32_e32 v142, v135, v135
	v_fmac_f32_e32 v143, v132, v132
	v_add_f32_e32 v138, v144, v139
	v_fmac_f32_e32 v142, v134, v134
	v_add_f32_e32 v138, v143, v138
	v_add_f32_e32 v138, v142, v138
	v_and_b32_e32 v139, 64, v222
	v_add_f32_e32 v144, v216, v138
	v_xor_b32_e32 v138, 16, v222
	v_add_u32_e32 v145, 64, v139
	v_cmp_lt_i32_e32 vcc, v138, v145
	v_pk_mul_f32 v[142:143], v[182:183], v[132:133]
	v_xor_b32_e32 v133, 32, v222
	v_cndmask_b32_e32 v138, v222, v138, vcc
	v_lshlrev_b32_e32 v138, 2, v138
	ds_bpermute_b32 v146, v138, v144
	v_cmp_lt_i32_e32 vcc, v133, v145
	v_pk_mul_f32 v[136:137], v[184:185], v[136:137]
	v_pk_mul_f32 v[138:139], v[186:187], v[134:135]
	v_cndmask_b32_e32 v133, v222, v133, vcc
	s_waitcnt lgkmcnt(0)
	v_add_f32_e32 v132, v144, v146
	v_lshlrev_b32_e32 v133, 2, v133
	ds_bpermute_b32 v133, v133, v132
	v_cvt_pk_bf16_f32 v134, v136, v137
	v_cvt_pk_bf16_f32 v135, v140, v141
	v_cvt_pk_bf16_f32 v136, v142, v143
	v_cvt_pk_bf16_f32 v137, v138, v139
	global_store_dwordx4 v[204:205], v[134:137], off offset:256
	s_and_saveexec_b64 s[4:5], s[36:37]
	s_cbranch_execz .LBB0_732
	v_lshl_add_u64 v[134:135], s[34:35], 2, v[168:169]
	s_waitcnt lgkmcnt(0)
	v_add_f32_e32 v132, v132, v133
	global_atomic_add_f32 v[134:135], v132, off

; __device__ __forceinline__ float bflo(unsigned w) { return __uint_as_float(w << 16); }
;     __device__ __forceinline__ void operator()(const pg8::f32x4 (&acc)[2][2][4][2], const pg8::Unit& u, int wr, int wc, int fr, int fq) const {
;     ...
;         for (int it = 0; it < 8; ++it) {
;             const int ai = it >> 2, m = it & 3;
;             const int rl = ai * 128 + wr * 64 + m * 16 + fr;
;             const size_t off = (size_t)(prow0 + rl) * DM + col0;
;             f32x4 cur[2][2];
; #pragma unroll
;             for (int bj = 0; bj < 2; ++bj) { cur[bj][0] = *(const f32x4*)(xin + off + bj * 128); cur[bj][1] = *(const f32x4*)(xin + off + bj * 128 + 4); }
;             float ss = 0.f;
; #pragma unroll
;             for (int bj = 0; bj < 2; ++bj) {
;                 f32x4 dl0 = gv[bj][0] * acc[ai][bj][m][0], dl1 = gv[bj][1] * acc[ai][bj][m][1];
;                 bf16* dp = d1 + (size_t)(u.pm * 256 + rl) * DM + col0 + bj * 128;
;                 if (dmode == 2) {
;                     const u32x4 dw = *(const u32x4*)dp;
;                     dl0 += (f32x4){bflo(dw[0]), bfhi(dw[0]), bflo(dw[1]), bfhi(dw[1])}; dl1 += (f32x4){bflo(dw[2]), bfhi(dw[2]), bflo(dw[3]), bfhi(dw[3])};
;                 }
;                 const f32x4 x0 = cur[bj][0] + dl0, x1 = cur[bj][1] + dl1;
;                 if (dmode == 1) { u32x4 dw; dw.x = cvt_pk_bf16(dl0[0], dl0[1]); dw.y = cvt_pk_bf16(dl0[2], dl0[3]); dw.z = cvt_pk_bf16(dl1[0], dl1[1]); dw.w = cvt_pk_bf16(dl1[2], dl1[3]); *(u32x4*)dp = dw; }
;                 else { *(f32x4*)(xout + off + bj * 128) = x0; *(f32x4*)(xout + off + bj * 128 + 4) = x1; }
;                 if (has_next) {
;                     ss += (x0[0] * x0[0] + x0[1] * x0[1]) + (x0[2] * x0[2] + x0[3] * x0[3]) + (x1[0] * x1[0] + x1[1] * x1[1]) + (x1[2] * x1[2] + x1[3] * x1[3]);
;                     const f32x4 y0 = x0 * gm[bj][0], y1 = x1 * gm[bj][1];
;                     u32x4 w; w.x = cvt_pk_bf16(y0[0], y0[1]); w.y = cvt_pk_bf16(y0[2], y0[3]); w.z = cvt_pk_bf16(y1[0], y1[1]); w.w = cvt_pk_bf16(y1[2], y1[3]);
;                     *(u32x4*)(xb + (size_t)(u.pm * 256 + rl) * DM + col0 + bj * 128) = w;
;                 }
;             }
;             if (has_next) {
;                 ss += __shfl_xor(ss, 16); ss += __shfl_xor(ss, 32);
;                 if (fq == 0) atomicAdd(rowss_next + u.pm * 256 + rl, ss);
;             }
;         }
.LBB0_733:
	s_nop 0
	v_add_u32_e32 v132, s6, v206
	s_waitcnt lgkmcnt(0)
	v_ashrrev_i32_e32 v133, 31, v132
	v_add_u32_e32 v142, s34, v206
	v_lshlrev_b64 v[132:133], 10, v[132:133]
	v_ashrrev_i32_e32 v143, 31, v142
	v_lshl_add_u64 v[132:133], v[132:133], 0, v[192:193]
	v_lshlrev_b64 v[142:143], 11, v[142:143]
	v_lshlrev_b64 v[140:141], 2, v[132:133]
	v_lshl_add_u64 v[144:145], s[78:79], 0, v[142:143]
	v_lshl_add_u64 v[136:137], s[74:75], 0, v[140:141]
	v_lshl_add_u64 v[144:145], v[192:193], 1, v[144:145]
	global_load_dwordx4 v[146:149], v[136:137], off offset:16
	global_load_dwordx4 v[150:153], v[136:137], off
	global_load_dwordx4 v[132:135], v[136:137], off offset:528
	s_nop 0
	global_load_dwordx4 v[136:139], v[136:137], off offset:512
	v_lshl_add_u64 v[142:143], s[86:87], 0, v[142:143]
	global_load_dwordx4 v[200:203], v[144:145], off
	global_load_dwordx4 v[240:243], v[144:145], off offset:256
	v_lshl_add_u64 v[140:141], s[58:59], 0, v[140:141]
	s_and_b64 vcc, exec, s[40:41]
	v_lshl_add_u64 v[142:143], v[192:193], 1, v[142:143]
	s_waitcnt vmcnt(0)
	v_lshlrev_b32_e32 v154, 16, v200
	v_and_b32_e32 v155, 0xffff0000, v200
	v_lshlrev_b32_e32 v200, 16, v201
	v_and_b32_e32 v201, 0xffff0000, v201
	v_pk_fma_f32 v[128:129], v[128:129], v[44:45], v[154:155]
	v_pk_fma_f32 v[130:131], v[130:131], v[46:47], v[200:201]
	v_lshlrev_b32_e32 v154, 16, v202
	v_and_b32_e32 v155, 0xffff0000, v202
	v_lshlrev_b32_e32 v200, 16, v203
	v_and_b32_e32 v201, 0xffff0000, v203
	v_pk_fma_f32 v[124:125], v[124:125], v[48:49], v[154:155]
	v_pk_fma_f32 v[126:127], v[126:127], v[50:51], v[200:201]
	v_pk_add_f32 v[130:131], v[152:153], v[130:131]
	v_pk_add_f32 v[128:129], v[150:151], v[128:129]
	v_pk_add_f32 v[126:127], v[148:149], v[126:127]
	v_pk_add_f32 v[124:125], v[146:147], v[124:125]
	v_mov_b32_e32 v146, 0
	global_store_dwordx4 v[140:141], v[128:131], off
	global_store_dwordx4 v[140:141], v[124:127], off offset:16
	s_cbranch_vccnz .LBB0_735
	v_pk_mul_f32 v[146:147], v[130:131], v[130:131]
	v_pk_mul_f32 v[148:149], v[128:129], v[128:129]
	v_pk_mul_f32 v[130:131], v[196:197], v[130:131]
	v_pk_mov_b32 v[150:151], v[148:149], v[146:147] op_sel:[1,0]
	v_mov_b32_e32 v149, v147
	v_pk_add_f32 v[146:147], v[150:151], v[148:149]
	v_pk_mul_f32 v[148:149], v[126:127], v[126:127]
	v_pk_mul_f32 v[150:151], v[124:125], v[124:125]
	v_mov_b32_e32 v152, v148
	v_mov_b32_e32 v153, v150
	v_mov_b32_e32 v150, v149
	v_pk_add_f32 v[148:149], v[152:153], v[150:151]
	v_add_f32_e32 v146, v146, v147
	v_add_f32_e32 v146, v149, v146
	v_add_f32_e32 v146, v148, v146
	v_pk_mul_f32 v[128:129], v[194:195], v[128:129]
	v_pk_mul_f32 v[148:149], v[198:199], v[126:127]
	v_pk_mul_f32 v[126:127], v[190:191], v[124:125]
	v_cvt_pk_bf16_f32 v124, v128, v129
	v_cvt_pk_bf16_f32 v125, v130, v131
	v_cvt_pk_bf16_f32 v126, v126, v127
	v_cvt_pk_bf16_f32 v127, v148, v149
	global_store_dwordx4 v[142:143], v[124:127], off
.LBB0_735:
	s_and_b64 vcc, exec, s[40:41]
	s_nop 1
	v_mov_b64_e32 v[124:125], v[240:241]
	v_mov_b64_e32 v[126:127], v[242:243]
	v_lshlrev_b32_e32 v128, 16, v124
	v_and_b32_e32 v129, 0xffff0000, v124
	v_lshlrev_b32_e32 v124, 16, v125
	v_and_b32_e32 v125, 0xffff0000, v125
	v_pk_fma_f32 v[122:123], v[122:123], v[30:31], v[124:125]
	v_lshlrev_b32_e32 v124, 16, v126
	v_and_b32_e32 v125, 0xffff0000, v126
	v_lshlrev_b32_e32 v126, 16, v127
	v_and_b32_e32 v127, 0xffff0000, v127
	v_pk_fma_f32 v[120:121], v[120:121], v[28:29], v[128:129]
	v_pk_fma_f32 v[116:117], v[116:117], v[40:41], v[124:125]
	v_pk_fma_f32 v[118:119], v[118:119], v[42:43], v[126:127]
	v_pk_add_f32 v[122:123], v[138:139], v[122:123]
	v_pk_add_f32 v[120:121], v[136:137], v[120:121]
	v_pk_add_f32 v[118:119], v[134:135], v[118:119]
	v_pk_add_f32 v[116:117], v[132:133], v[116:117]
	global_store_dwordx4 v[140:141], v[120:123], off offset:512
	global_store_dwordx4 v[140:141], v[116:119], off offset:528
	s_cbranch_vccnz .LBB0_739
	v_pk_mul_f32 v[124:125], v[188:189], v[122:123]
	v_mul_f32_e32 v128, v121, v121
	v_mul_f32_e32 v123, v123, v123
	v_mul_f32_e32 v127, v117, v117
	v_fmac_f32_e32 v128, v120, v120
	v_fmac_f32_e32 v123, v122, v122
	v_mul_f32_e32 v126, v119, v119
	v_fmac_f32_e32 v127, v116, v116
	v_add_f32_e32 v122, v128, v123
	v_fmac_f32_e32 v126, v118, v118
	v_add_f32_e32 v122, v127, v122
	v_add_f32_e32 v122, v126, v122
	v_and_b32_e32 v123, 64, v222
	v_add_f32_e32 v128, v146, v122
	v_xor_b32_e32 v122, 16, v222
	v_add_u32_e32 v129, 64, v123
	v_cmp_lt_i32_e32 vcc, v122, v129
	v_pk_mul_f32 v[126:127], v[182:183], v[116:117]
	v_xor_b32_e32 v117, 32, v222
	v_cndmask_b32_e32 v122, v222, v122, vcc
	v_lshlrev_b32_e32 v122, 2, v122
	ds_bpermute_b32 v130, v122, v128
	v_cmp_lt_i32_e32 vcc, v117, v129
	v_pk_mul_f32 v[120:121], v[184:185], v[120:121]
	v_pk_mul_f32 v[122:123], v[186:187], v[118:119]
	v_cndmask_b32_e32 v117, v222, v117, vcc
	s_waitcnt lgkmcnt(0)
	v_add_f32_e32 v116, v128, v130
	v_lshlrev_b32_e32 v117, 2, v117
	ds_bpermute_b32 v117, v117, v116
	v_cvt_pk_bf16_f32 v118, v120, v121
	v_cvt_pk_bf16_f32 v119, v124, v125
	v_cvt_pk_bf16_f32 v120, v126, v127
	v_cvt_pk_bf16_f32 v121, v122, v123
	global_store_dwordx4 v[142:143], v[118:121], off offset:256
	s_and_saveexec_b64 s[4:5], s[36:37]
	s_cbranch_execz .LBB0_738
	v_lshl_add_u64 v[118:119], s[34:35], 2, v[168:169]
	s_waitcnt lgkmcnt(0)
	v_add_f32_e32 v116, v116, v117
	global_atomic_add_f32 v[118:119], v116, off offset:64

; __device__ __forceinline__ float bflo(unsigned w) { return __uint_as_float(w << 16); }
;     __device__ __forceinline__ void operator()(const pg8::f32x4 (&acc)[2][2][4][2], const pg8::Unit& u, int wr, int wc, int fr, int fq) const {
;     ...
;         for (int it = 0; it < 8; ++it) {
;             const int ai = it >> 2, m = it & 3;
;             const int rl = ai * 128 + wr * 64 + m * 16 + fr;
;             const size_t off = (size_t)(prow0 + rl) * DM + col0;
;             f32x4 cur[2][2];
; #pragma unroll
;             for (int bj = 0; bj < 2; ++bj) { cur[bj][0] = *(const f32x4*)(xin + off + bj * 128); cur[bj][1] = *(const f32x4*)(xin + off + bj * 128 + 4); }
;             float ss = 0.f;
; #pragma unroll
;             for (int bj = 0; bj < 2; ++bj) {
;                 f32x4 dl0 = gv[bj][0] * acc[ai][bj][m][0], dl1 = gv[bj][1] * acc[ai][bj][m][1];
;                 bf16* dp = d1 + (size_t)(u.pm * 256 + rl) * DM + col0 + bj * 128;
;                 if (dmode == 2) {
;                     const u32x4 dw = *(const u32x4*)dp;
;                     dl0 += (f32x4){bflo(dw[0]), bfhi(dw[0]), bflo(dw[1]), bfhi(dw[1])}; dl1 += (f32x4){bflo(dw[2]), bfhi(dw[2]), bflo(dw[3]), bfhi(dw[3])};
;                 }
;                 const f32x4 x0 = cur[bj][0] + dl0, x1 = cur[bj][1] + dl1;
;                 if (dmode == 1) { u32x4 dw; dw.x = cvt_pk_bf16(dl0[0], dl0[1]); dw.y = cvt_pk_bf16(dl0[2], dl0[3]); dw.z = cvt_pk_bf16(dl1[0], dl1[1]); dw.w = cvt_pk_bf16(dl1[2], dl1[3]); *(u32x4*)dp = dw; }
;                 else { *(f32x4*)(xout + off + bj * 128) = x0; *(f32x4*)(xout + off + bj * 128 + 4) = x1; }
;                 if (has_next) {
;                     ss += (x0[0] * x0[0] + x0[1] * x0[1]) + (x0[2] * x0[2] + x0[3] * x0[3]) + (x1[0] * x1[0] + x1[1] * x1[1]) + (x1[2] * x1[2] + x1[3] * x1[3]);
;                     const f32x4 y0 = x0 * gm[bj][0], y1 = x1 * gm[bj][1];
;                     u32x4 w; w.x = cvt_pk_bf16(y0[0], y0[1]); w.y = cvt_pk_bf16(y0[2], y0[3]); w.z = cvt_pk_bf16(y1[0], y1[1]); w.w = cvt_pk_bf16(y1[2], y1[3]);
;                     *(u32x4*)(xb + (size_t)(u.pm * 256 + rl) * DM + col0 + bj * 128) = w;
;                 }
;             }
;             if (has_next) {
;                 ss += __shfl_xor(ss, 16); ss += __shfl_xor(ss, 32);
;                 if (fq == 0) atomicAdd(rowss_next + u.pm * 256 + rl, ss);
;             }
;         }
.LBB0_739:
	s_nop 0
	v_add_u32_e32 v116, s6, v207
	s_waitcnt lgkmcnt(0)
	v_ashrrev_i32_e32 v117, 31, v116
	v_add_u32_e32 v126, s34, v207
	v_lshlrev_b64 v[116:117], 10, v[116:117]
	v_ashrrev_i32_e32 v127, 31, v126
	v_lshl_add_u64 v[116:117], v[116:117], 0, v[192:193]
	v_lshlrev_b64 v[126:127], 11, v[126:127]
	v_lshlrev_b64 v[124:125], 2, v[116:117]
	v_lshl_add_u64 v[128:129], s[78:79], 0, v[126:127]
	v_lshl_add_u64 v[120:121], s[74:75], 0, v[124:125]
	v_lshl_add_u64 v[128:129], v[192:193], 1, v[128:129]
	global_load_dwordx4 v[130:133], v[120:121], off offset:16
	global_load_dwordx4 v[134:137], v[120:121], off
	global_load_dwordx4 v[116:119], v[120:121], off offset:528
	s_nop 0
	global_load_dwordx4 v[120:123], v[120:121], off offset:512
	v_lshl_add_u64 v[126:127], s[86:87], 0, v[126:127]
	global_load_dwordx4 v[138:141], v[128:129], off
	global_load_dwordx4 v[240:243], v[128:129], off offset:256
	v_lshl_add_u64 v[124:125], s[58:59], 0, v[124:125]
	s_and_b64 vcc, exec, s[40:41]
	v_lshl_add_u64 v[126:127], v[192:193], 1, v[126:127]
	s_waitcnt vmcnt(0)
	v_lshlrev_b32_e32 v142, 16, v138
	v_and_b32_e32 v143, 0xffff0000, v138
	v_lshlrev_b32_e32 v138, 16, v139
	v_and_b32_e32 v139, 0xffff0000, v139
	v_pk_fma_f32 v[114:115], v[114:115], v[46:47], v[138:139]
	v_lshlrev_b32_e32 v138, 16, v140
	v_and_b32_e32 v139, 0xffff0000, v140
	v_lshlrev_b32_e32 v140, 16, v141
	v_and_b32_e32 v141, 0xffff0000, v141
	v_pk_fma_f32 v[112:113], v[112:113], v[44:45], v[142:143]
	v_pk_fma_f32 v[108:109], v[108:109], v[48:49], v[138:139]
	v_pk_fma_f32 v[110:111], v[110:111], v[50:51], v[140:141]
	v_pk_add_f32 v[114:115], v[136:137], v[114:115]
	v_pk_add_f32 v[112:113], v[134:135], v[112:113]
	v_pk_add_f32 v[110:111], v[132:133], v[110:111]
	v_pk_add_f32 v[108:109], v[130:131], v[108:109]
	v_mov_b32_e32 v130, 0
	global_store_dwordx4 v[124:125], v[112:115], off
	global_store_dwordx4 v[124:125], v[108:111], off offset:16
	s_cbranch_vccnz .LBB0_741
	v_pk_mul_f32 v[130:131], v[114:115], v[114:115]
	v_pk_mul_f32 v[132:133], v[112:113], v[112:113]
	v_pk_mul_f32 v[114:115], v[196:197], v[114:115]
	v_pk_mov_b32 v[134:135], v[132:133], v[130:131] op_sel:[1,0]
	v_mov_b32_e32 v133, v131
	v_pk_add_f32 v[130:131], v[134:135], v[132:133]
	v_pk_mul_f32 v[132:133], v[110:111], v[110:111]
	v_pk_mul_f32 v[134:135], v[108:109], v[108:109]
	v_mov_b32_e32 v136, v132
	v_mov_b32_e32 v137, v134
	v_mov_b32_e32 v134, v133
	v_pk_add_f32 v[132:133], v[136:137], v[134:135]
	v_add_f32_e32 v130, v130, v131
	v_add_f32_e32 v130, v133, v130
	v_add_f32_e32 v130, v132, v130
	v_pk_mul_f32 v[112:113], v[194:195], v[112:113]
	v_pk_mul_f32 v[132:133], v[198:199], v[110:111]
	v_pk_mul_f32 v[110:111], v[190:191], v[108:109]
	v_cvt_pk_bf16_f32 v108, v112, v113
	v_cvt_pk_bf16_f32 v109, v114, v115
	v_cvt_pk_bf16_f32 v110, v110, v111
	v_cvt_pk_bf16_f32 v111, v132, v133
	global_store_dwordx4 v[126:127], v[108:111], off
.LBB0_741:
	s_and_b64 vcc, exec, s[40:41]
	s_nop 1
	v_mov_b64_e32 v[108:109], v[240:241]
	v_mov_b64_e32 v[110:111], v[242:243]
	v_lshlrev_b32_e32 v112, 16, v108
	v_and_b32_e32 v113, 0xffff0000, v108
	v_lshlrev_b32_e32 v108, 16, v109
	v_and_b32_e32 v109, 0xffff0000, v109
	v_pk_fma_f32 v[106:107], v[106:107], v[30:31], v[108:109]
	v_lshlrev_b32_e32 v108, 16, v110
	v_and_b32_e32 v109, 0xffff0000, v110
	v_lshlrev_b32_e32 v110, 16, v111
	v_and_b32_e32 v111, 0xffff0000, v111
	v_pk_fma_f32 v[104:105], v[104:105], v[28:29], v[112:113]
	v_pk_fma_f32 v[100:101], v[100:101], v[40:41], v[108:109]
	v_pk_fma_f32 v[102:103], v[102:103], v[42:43], v[110:111]
	v_pk_add_f32 v[106:107], v[122:123], v[106:107]
	v_pk_add_f32 v[104:105], v[120:121], v[104:105]
	v_pk_add_f32 v[102:103], v[118:119], v[102:103]
	v_pk_add_f32 v[100:101], v[116:117], v[100:101]
	global_store_dwordx4 v[124:125], v[104:107], off offset:512
	global_store_dwordx4 v[124:125], v[100:103], off offset:528
	s_cbranch_vccnz .LBB0_745
	v_pk_mul_f32 v[108:109], v[188:189], v[106:107]
	v_mul_f32_e32 v112, v105, v105
	v_mul_f32_e32 v107, v107, v107
	v_mul_f32_e32 v111, v101, v101
	v_fmac_f32_e32 v112, v104, v104
	v_fmac_f32_e32 v107, v106, v106
	v_mul_f32_e32 v110, v103, v103
	v_fmac_f32_e32 v111, v100, v100
	v_add_f32_e32 v106, v112, v107
	v_fmac_f32_e32 v110, v102, v102
	v_add_f32_e32 v106, v111, v106
	v_add_f32_e32 v106, v110, v106
	v_and_b32_e32 v107, 64, v222
	v_add_f32_e32 v112, v130, v106
	v_xor_b32_e32 v106, 16, v222
	v_add_u32_e32 v113, 64, v107
	v_cmp_lt_i32_e32 vcc, v106, v113
	v_pk_mul_f32 v[110:111], v[182:183], v[100:101]
	v_xor_b32_e32 v101, 32, v222
	v_cndmask_b32_e32 v106, v222, v106, vcc
	v_lshlrev_b32_e32 v106, 2, v106
	ds_bpermute_b32 v114, v106, v112
	v_cmp_lt_i32_e32 vcc, v101, v113
	v_pk_mul_f32 v[104:105], v[184:185], v[104:105]
	v_pk_mul_f32 v[106:107], v[186:187], v[102:103]
	v_cndmask_b32_e32 v101, v222, v101, vcc
	s_waitcnt lgkmcnt(0)
	v_add_f32_e32 v100, v112, v114
	v_lshlrev_b32_e32 v101, 2, v101
	ds_bpermute_b32 v101, v101, v100
	v_cvt_pk_bf16_f32 v102, v104, v105
	v_cvt_pk_bf16_f32 v103, v108, v109
	v_cvt_pk_bf16_f32 v104, v110, v111
	v_cvt_pk_bf16_f32 v105, v106, v107
	global_store_dwordx4 v[126:127], v[102:105], off offset:256
	s_and_saveexec_b64 s[4:5], s[36:37]
	s_cbranch_execz .LBB0_744
	v_lshl_add_u64 v[102:103], s[34:35], 2, v[168:169]
	s_waitcnt lgkmcnt(0)
	v_add_f32_e32 v100, v100, v101
	global_atomic_add_f32 v[102:103], v100, off offset:128

; __device__ __forceinline__ float bflo(unsigned w) { return __uint_as_float(w << 16); }
;     __device__ __forceinline__ void operator()(const pg8::f32x4 (&acc)[2][2][4][2], const pg8::Unit& u, int wr, int wc, int fr, int fq) const {
;     ...
;         for (int it = 0; it < 8; ++it) {
;             const int ai = it >> 2, m = it & 3;
;             const int rl = ai * 128 + wr * 64 + m * 16 + fr;
;             const size_t off = (size_t)(prow0 + rl) * DM + col0;
;             f32x4 cur[2][2];
; #pragma unroll
;             for (int bj = 0; bj < 2; ++bj) { cur[bj][0] = *(const f32x4*)(xin + off + bj * 128); cur[bj][1] = *(const f32x4*)(xin + off + bj * 128 + 4); }
;             float ss = 0.f;
; #pragma unroll
;             for (int bj = 0; bj < 2; ++bj) {
;                 f32x4 dl0 = gv[bj][0] * acc[ai][bj][m][0], dl1 = gv[bj][1] * acc[ai][bj][m][1];
;                 bf16* dp = d1 + (size_t)(u.pm * 256 + rl) * DM + col0 + bj * 128;
;                 if (dmode == 2) {
;                     const u32x4 dw = *(const u32x4*)dp;
;                     dl0 += (f32x4){bflo(dw[0]), bfhi(dw[0]), bflo(dw[1]), bfhi(dw[1])}; dl1 += (f32x4){bflo(dw[2]), bfhi(dw[2]), bflo(dw[3]), bfhi(dw[3])};
;                 }
;                 const f32x4 x0 = cur[bj][0] + dl0, x1 = cur[bj][1] + dl1;
;                 if (dmode == 1) { u32x4 dw; dw.x = cvt_pk_bf16(dl0[0], dl0[1]); dw.y = cvt_pk_bf16(dl0[2], dl0[3]); dw.z = cvt_pk_bf16(dl1[0], dl1[1]); dw.w = cvt_pk_bf16(dl1[2], dl1[3]); *(u32x4*)dp = dw; }
;                 else { *(f32x4*)(xout + off + bj * 128) = x0; *(f32x4*)(xout + off + bj * 128 + 4) = x1; }
;                 if (has_next) {
;                     ss += (x0[0] * x0[0] + x0[1] * x0[1]) + (x0[2] * x0[2] + x0[3] * x0[3]) + (x1[0] * x1[0] + x1[1] * x1[1]) + (x1[2] * x1[2] + x1[3] * x1[3]);
;                     const f32x4 y0 = x0 * gm[bj][0], y1 = x1 * gm[bj][1];
;                     u32x4 w; w.x = cvt_pk_bf16(y0[0], y0[1]); w.y = cvt_pk_bf16(y0[2], y0[3]); w.z = cvt_pk_bf16(y1[0], y1[1]); w.w = cvt_pk_bf16(y1[2], y1[3]);
;                     *(u32x4*)(xb + (size_t)(u.pm * 256 + rl) * DM + col0 + bj * 128) = w;
;                 }
;             }
;             if (has_next) {
;                 ss += __shfl_xor(ss, 16); ss += __shfl_xor(ss, 32);
;                 if (fq == 0) atomicAdd(rowss_next + u.pm * 256 + rl, ss);
;             }
;         }
.LBB0_745:
	s_nop 0
	v_add_u32_e32 v100, s6, v208
	s_waitcnt lgkmcnt(0)
	v_ashrrev_i32_e32 v101, 31, v100
	v_add_u32_e32 v110, s34, v208
	v_lshlrev_b64 v[100:101], 10, v[100:101]
	v_ashrrev_i32_e32 v111, 31, v110
	v_lshl_add_u64 v[100:101], v[100:101], 0, v[192:193]
	v_lshlrev_b64 v[110:111], 11, v[110:111]
	v_lshlrev_b64 v[108:109], 2, v[100:101]
	v_lshl_add_u64 v[112:113], s[78:79], 0, v[110:111]
	v_lshl_add_u64 v[104:105], s[74:75], 0, v[108:109]
	v_lshl_add_u64 v[112:113], v[192:193], 1, v[112:113]
	global_load_dwordx4 v[114:117], v[104:105], off offset:16
	global_load_dwordx4 v[118:121], v[104:105], off
	global_load_dwordx4 v[100:103], v[104:105], off offset:528
	s_nop 0
	global_load_dwordx4 v[104:107], v[104:105], off offset:512
	v_lshl_add_u64 v[110:111], s[86:87], 0, v[110:111]
	global_load_dwordx4 v[122:125], v[112:113], off
	global_load_dwordx4 v[240:243], v[112:113], off offset:256
	v_lshl_add_u64 v[108:109], s[58:59], 0, v[108:109]
	s_and_b64 vcc, exec, s[40:41]
	v_lshl_add_u64 v[110:111], v[192:193], 1, v[110:111]
	s_waitcnt vmcnt(0)
	v_lshlrev_b32_e32 v126, 16, v122
	v_and_b32_e32 v127, 0xffff0000, v122
	v_lshlrev_b32_e32 v122, 16, v123
	v_and_b32_e32 v123, 0xffff0000, v123
	v_pk_fma_f32 v[98:99], v[98:99], v[46:47], v[122:123]
	v_lshlrev_b32_e32 v122, 16, v124
	v_and_b32_e32 v123, 0xffff0000, v124
	v_lshlrev_b32_e32 v124, 16, v125
	v_and_b32_e32 v125, 0xffff0000, v125
	v_pk_fma_f32 v[96:97], v[96:97], v[44:45], v[126:127]
	v_pk_fma_f32 v[92:93], v[92:93], v[48:49], v[122:123]
	v_pk_fma_f32 v[94:95], v[94:95], v[50:51], v[124:125]
	v_pk_add_f32 v[98:99], v[120:121], v[98:99]
	v_pk_add_f32 v[96:97], v[118:119], v[96:97]
	v_pk_add_f32 v[94:95], v[116:117], v[94:95]
	v_pk_add_f32 v[92:93], v[114:115], v[92:93]
	v_mov_b32_e32 v114, 0
	global_store_dwordx4 v[108:109], v[96:99], off
	global_store_dwordx4 v[108:109], v[92:95], off offset:16
	s_cbranch_vccnz .LBB0_747
	v_pk_mul_f32 v[114:115], v[98:99], v[98:99]
	v_pk_mul_f32 v[116:117], v[96:97], v[96:97]
	v_pk_mul_f32 v[98:99], v[196:197], v[98:99]
	v_pk_mov_b32 v[118:119], v[116:117], v[114:115] op_sel:[1,0]
	v_mov_b32_e32 v117, v115
	v_pk_add_f32 v[114:115], v[118:119], v[116:117]
	v_pk_mul_f32 v[116:117], v[94:95], v[94:95]
	v_pk_mul_f32 v[118:119], v[92:93], v[92:93]
	v_mov_b32_e32 v120, v116
	v_mov_b32_e32 v121, v118
	v_mov_b32_e32 v118, v117
	v_pk_add_f32 v[116:117], v[120:121], v[118:119]
	v_add_f32_e32 v114, v114, v115
	v_add_f32_e32 v114, v117, v114
	v_add_f32_e32 v114, v116, v114
	v_pk_mul_f32 v[96:97], v[194:195], v[96:97]
	v_pk_mul_f32 v[116:117], v[198:199], v[94:95]
	v_pk_mul_f32 v[94:95], v[190:191], v[92:93]
	v_cvt_pk_bf16_f32 v92, v96, v97
	v_cvt_pk_bf16_f32 v93, v98, v99
	v_cvt_pk_bf16_f32 v94, v94, v95
	v_cvt_pk_bf16_f32 v95, v116, v117
	global_store_dwordx4 v[110:111], v[92:95], off
.LBB0_747:
	s_and_b64 vcc, exec, s[40:41]
	s_nop 1
	v_mov_b64_e32 v[92:93], v[240:241]
	v_mov_b64_e32 v[94:95], v[242:243]
	v_lshlrev_b32_e32 v96, 16, v92
	v_and_b32_e32 v97, 0xffff0000, v92
	v_lshlrev_b32_e32 v92, 16, v93
	v_and_b32_e32 v93, 0xffff0000, v93
	v_pk_fma_f32 v[90:91], v[90:91], v[30:31], v[92:93]
	v_lshlrev_b32_e32 v92, 16, v94
	v_and_b32_e32 v93, 0xffff0000, v94
	v_lshlrev_b32_e32 v94, 16, v95
	v_and_b32_e32 v95, 0xffff0000, v95
	v_pk_fma_f32 v[88:89], v[88:89], v[28:29], v[96:97]
	v_pk_fma_f32 v[84:85], v[84:85], v[40:41], v[92:93]
	v_pk_fma_f32 v[86:87], v[86:87], v[42:43], v[94:95]
	v_pk_add_f32 v[90:91], v[106:107], v[90:91]
	v_pk_add_f32 v[88:89], v[104:105], v[88:89]
	v_pk_add_f32 v[86:87], v[102:103], v[86:87]
	v_pk_add_f32 v[84:85], v[100:101], v[84:85]
	global_store_dwordx4 v[108:109], v[88:91], off offset:512
	global_store_dwordx4 v[108:109], v[84:87], off offset:528
	s_cbranch_vccnz .LBB0_751
	v_pk_mul_f32 v[92:93], v[188:189], v[90:91]
	v_mul_f32_e32 v96, v89, v89
	v_mul_f32_e32 v91, v91, v91
	v_mul_f32_e32 v95, v85, v85
	v_fmac_f32_e32 v96, v88, v88
	v_fmac_f32_e32 v91, v90, v90
	v_mul_f32_e32 v94, v87, v87
	v_fmac_f32_e32 v95, v84, v84
	v_add_f32_e32 v90, v96, v91
	v_fmac_f32_e32 v94, v86, v86
	v_add_f32_e32 v90, v95, v90
	v_add_f32_e32 v90, v94, v90
	v_and_b32_e32 v91, 64, v222
	v_add_f32_e32 v96, v114, v90
	v_xor_b32_e32 v90, 16, v222
	v_add_u32_e32 v97, 64, v91
	v_cmp_lt_i32_e32 vcc, v90, v97
	v_pk_mul_f32 v[94:95], v[182:183], v[84:85]
	v_xor_b32_e32 v85, 32, v222
	v_cndmask_b32_e32 v90, v222, v90, vcc
	v_lshlrev_b32_e32 v90, 2, v90
	ds_bpermute_b32 v98, v90, v96
	v_cmp_lt_i32_e32 vcc, v85, v97
	v_pk_mul_f32 v[88:89], v[184:185], v[88:89]
	v_pk_mul_f32 v[90:91], v[186:187], v[86:87]
	v_cndmask_b32_e32 v85, v222, v85, vcc
	s_waitcnt lgkmcnt(0)
	v_add_f32_e32 v84, v96, v98
	v_lshlrev_b32_e32 v85, 2, v85
	ds_bpermute_b32 v85, v85, v84
	v_cvt_pk_bf16_f32 v86, v88, v89
	v_cvt_pk_bf16_f32 v87, v92, v93
	v_cvt_pk_bf16_f32 v88, v94, v95
	v_cvt_pk_bf16_f32 v89, v90, v91
	global_store_dwordx4 v[110:111], v[86:89], off offset:256
	s_and_saveexec_b64 s[4:5], s[36:37]
	s_cbranch_execz .LBB0_750
	v_lshl_add_u64 v[86:87], s[34:35], 2, v[168:169]
	s_waitcnt lgkmcnt(0)
	v_add_f32_e32 v84, v84, v85
	global_atomic_add_f32 v[86:87], v84, off offset:192

; __device__ __forceinline__ float bflo(unsigned w) { return __uint_as_float(w << 16); }
;     __device__ __forceinline__ void operator()(const pg8::f32x4 (&acc)[2][2][4][2], const pg8::Unit& u, int wr, int wc, int fr, int fq) const {
;     ...
;         for (int it = 0; it < 8; ++it) {
;             const int ai = it >> 2, m = it & 3;
;             const int rl = ai * 128 + wr * 64 + m * 16 + fr;
;             const size_t off = (size_t)(prow0 + rl) * DM + col0;
;             f32x4 cur[2][2];
; #pragma unroll
;             for (int bj = 0; bj < 2; ++bj) { cur[bj][0] = *(const f32x4*)(xin + off + bj * 128); cur[bj][1] = *(const f32x4*)(xin + off + bj * 128 + 4); }
;             float ss = 0.f;
; #pragma unroll
;             for (int bj = 0; bj < 2; ++bj) {
;                 f32x4 dl0 = gv[bj][0] * acc[ai][bj][m][0], dl1 = gv[bj][1] * acc[ai][bj][m][1];
;                 bf16* dp = d1 + (size_t)(u.pm * 256 + rl) * DM + col0 + bj * 128;
;                 if (dmode == 2) {
;                     const u32x4 dw = *(const u32x4*)dp;
;                     dl0 += (f32x4){bflo(dw[0]), bfhi(dw[0]), bflo(dw[1]), bfhi(dw[1])}; dl1 += (f32x4){bflo(dw[2]), bfhi(dw[2]), bflo(dw[3]), bfhi(dw[3])};
;                 }
;                 const f32x4 x0 = cur[bj][0] + dl0, x1 = cur[bj][1] + dl1;
;                 if (dmode == 1) { u32x4 dw; dw.x = cvt_pk_bf16(dl0[0], dl0[1]); dw.y = cvt_pk_bf16(dl0[2], dl0[3]); dw.z = cvt_pk_bf16(dl1[0], dl1[1]); dw.w = cvt_pk_bf16(dl1[2], dl1[3]); *(u32x4*)dp = dw; }
;                 else { *(f32x4*)(xout + off + bj * 128) = x0; *(f32x4*)(xout + off + bj * 128 + 4) = x1; }
;                 if (has_next) {
;                     ss += (x0[0] * x0[0] + x0[1] * x0[1]) + (x0[2] * x0[2] + x0[3] * x0[3]) + (x1[0] * x1[0] + x1[1] * x1[1]) + (x1[2] * x1[2] + x1[3] * x1[3]);
;                     const f32x4 y0 = x0 * gm[bj][0], y1 = x1 * gm[bj][1];
;                     u32x4 w; w.x = cvt_pk_bf16(y0[0], y0[1]); w.y = cvt_pk_bf16(y0[2], y0[3]); w.z = cvt_pk_bf16(y1[0], y1[1]); w.w = cvt_pk_bf16(y1[2], y1[3]);
;                     *(u32x4*)(xb + (size_t)(u.pm * 256 + rl) * DM + col0 + bj * 128) = w;
;                 }
;             }
;             if (has_next) {
;                 ss += __shfl_xor(ss, 16); ss += __shfl_xor(ss, 32);
;                 if (fq == 0) atomicAdd(rowss_next + u.pm * 256 + rl, ss);
;             }
;         }
.LBB0_751:
	s_nop 0
	v_add_u32_e32 v84, s6, v210
	s_waitcnt lgkmcnt(0)
	v_ashrrev_i32_e32 v85, 31, v84
	v_add_u32_e32 v94, s34, v210
	v_lshlrev_b64 v[84:85], 10, v[84:85]
	v_ashrrev_i32_e32 v95, 31, v94
	v_lshl_add_u64 v[84:85], v[84:85], 0, v[192:193]
	v_lshlrev_b64 v[94:95], 11, v[94:95]
	v_lshlrev_b64 v[92:93], 2, v[84:85]
	v_lshl_add_u64 v[96:97], s[78:79], 0, v[94:95]
	v_lshl_add_u64 v[88:89], s[74:75], 0, v[92:93]
	v_lshl_add_u64 v[96:97], v[192:193], 1, v[96:97]
	global_load_dwordx4 v[98:101], v[88:89], off offset:16
	global_load_dwordx4 v[102:105], v[88:89], off
	global_load_dwordx4 v[84:87], v[88:89], off offset:528
	s_nop 0
	global_load_dwordx4 v[88:91], v[88:89], off offset:512
	v_lshl_add_u64 v[94:95], s[86:87], 0, v[94:95]
	global_load_dwordx4 v[106:109], v[96:97], off
	global_load_dwordx4 v[240:243], v[96:97], off offset:256
	v_lshl_add_u64 v[92:93], s[58:59], 0, v[92:93]
	s_and_b64 vcc, exec, s[40:41]
	v_lshl_add_u64 v[94:95], v[192:193], 1, v[94:95]
	s_waitcnt vmcnt(0)
	v_lshlrev_b32_e32 v110, 16, v106
	v_and_b32_e32 v111, 0xffff0000, v106
	v_lshlrev_b32_e32 v106, 16, v107
	v_and_b32_e32 v107, 0xffff0000, v107
	v_pk_fma_f32 v[82:83], v[82:83], v[46:47], v[106:107]
	v_lshlrev_b32_e32 v106, 16, v108
	v_and_b32_e32 v107, 0xffff0000, v108
	v_lshlrev_b32_e32 v108, 16, v109
	v_and_b32_e32 v109, 0xffff0000, v109
	v_pk_fma_f32 v[80:81], v[80:81], v[44:45], v[110:111]
	v_pk_fma_f32 v[76:77], v[76:77], v[48:49], v[106:107]
	v_pk_fma_f32 v[78:79], v[78:79], v[50:51], v[108:109]
	v_pk_add_f32 v[82:83], v[104:105], v[82:83]
	v_pk_add_f32 v[80:81], v[102:103], v[80:81]
	v_pk_add_f32 v[78:79], v[100:101], v[78:79]
	v_pk_add_f32 v[76:77], v[98:99], v[76:77]
	v_mov_b32_e32 v98, 0
	global_store_dwordx4 v[92:93], v[80:83], off
	global_store_dwordx4 v[92:93], v[76:79], off offset:16
	s_cbranch_vccnz .LBB0_753
	v_pk_mul_f32 v[98:99], v[82:83], v[82:83]
	v_pk_mul_f32 v[100:101], v[80:81], v[80:81]
	v_pk_mul_f32 v[82:83], v[196:197], v[82:83]
	v_pk_mov_b32 v[102:103], v[100:101], v[98:99] op_sel:[1,0]
	v_mov_b32_e32 v101, v99
	v_pk_add_f32 v[98:99], v[102:103], v[100:101]
	v_pk_mul_f32 v[100:101], v[78:79], v[78:79]
	v_pk_mul_f32 v[102:103], v[76:77], v[76:77]
	v_mov_b32_e32 v104, v100
	v_mov_b32_e32 v105, v102
	v_mov_b32_e32 v102, v101
	v_pk_add_f32 v[100:101], v[104:105], v[102:103]
	v_add_f32_e32 v98, v98, v99
	v_add_f32_e32 v98, v101, v98
	v_add_f32_e32 v98, v100, v98
	v_pk_mul_f32 v[80:81], v[194:195], v[80:81]
	v_pk_mul_f32 v[100:101], v[198:199], v[78:79]
	v_pk_mul_f32 v[78:79], v[190:191], v[76:77]
	v_cvt_pk_bf16_f32 v76, v80, v81
	v_cvt_pk_bf16_f32 v77, v82, v83
	v_cvt_pk_bf16_f32 v78, v78, v79
	v_cvt_pk_bf16_f32 v79, v100, v101
	global_store_dwordx4 v[94:95], v[76:79], off
.LBB0_753:
	s_and_b64 vcc, exec, s[40:41]
	s_nop 1
	v_mov_b64_e32 v[76:77], v[240:241]
	v_mov_b64_e32 v[78:79], v[242:243]
	v_lshlrev_b32_e32 v80, 16, v76
	v_and_b32_e32 v81, 0xffff0000, v76
	v_lshlrev_b32_e32 v76, 16, v77
	v_and_b32_e32 v77, 0xffff0000, v77
	v_pk_fma_f32 v[74:75], v[74:75], v[30:31], v[76:77]
	v_lshlrev_b32_e32 v76, 16, v78
	v_and_b32_e32 v77, 0xffff0000, v78
	v_lshlrev_b32_e32 v78, 16, v79
	v_and_b32_e32 v79, 0xffff0000, v79
	v_pk_fma_f32 v[72:73], v[72:73], v[28:29], v[80:81]
	v_pk_fma_f32 v[68:69], v[68:69], v[40:41], v[76:77]
	v_pk_fma_f32 v[70:71], v[70:71], v[42:43], v[78:79]
	v_pk_add_f32 v[74:75], v[90:91], v[74:75]
	v_pk_add_f32 v[72:73], v[88:89], v[72:73]
	v_pk_add_f32 v[70:71], v[86:87], v[70:71]
	v_pk_add_f32 v[68:69], v[84:85], v[68:69]
	global_store_dwordx4 v[92:93], v[72:75], off offset:512
	global_store_dwordx4 v[92:93], v[68:71], off offset:528
	s_cbranch_vccnz .LBB0_757
	v_pk_mul_f32 v[76:77], v[188:189], v[74:75]
	v_mul_f32_e32 v80, v73, v73
	v_mul_f32_e32 v75, v75, v75
	v_mul_f32_e32 v79, v69, v69
	v_fmac_f32_e32 v80, v72, v72
	v_fmac_f32_e32 v75, v74, v74
	v_mul_f32_e32 v78, v71, v71
	v_fmac_f32_e32 v79, v68, v68
	v_add_f32_e32 v74, v80, v75
	v_fmac_f32_e32 v78, v70, v70
	v_add_f32_e32 v74, v79, v74
	v_add_f32_e32 v74, v78, v74
	v_and_b32_e32 v75, 64, v222
	v_add_f32_e32 v80, v98, v74
	v_xor_b32_e32 v74, 16, v222
	v_add_u32_e32 v81, 64, v75
	v_cmp_lt_i32_e32 vcc, v74, v81
	v_pk_mul_f32 v[78:79], v[182:183], v[68:69]
	v_xor_b32_e32 v69, 32, v222
	v_cndmask_b32_e32 v74, v222, v74, vcc
	v_lshlrev_b32_e32 v74, 2, v74
	ds_bpermute_b32 v82, v74, v80
	v_cmp_lt_i32_e32 vcc, v69, v81
	v_pk_mul_f32 v[72:73], v[184:185], v[72:73]
	v_pk_mul_f32 v[74:75], v[186:187], v[70:71]
	v_cndmask_b32_e32 v69, v222, v69, vcc
	s_waitcnt lgkmcnt(0)
	v_add_f32_e32 v68, v80, v82
	v_lshlrev_b32_e32 v69, 2, v69
	ds_bpermute_b32 v69, v69, v68
	v_cvt_pk_bf16_f32 v70, v72, v73
	v_cvt_pk_bf16_f32 v71, v76, v77
	v_cvt_pk_bf16_f32 v72, v78, v79
	v_cvt_pk_bf16_f32 v73, v74, v75
	global_store_dwordx4 v[94:95], v[70:73], off offset:256
	s_and_saveexec_b64 s[4:5], s[36:37]
	s_cbranch_execz .LBB0_756
	v_lshl_add_u64 v[70:71], s[34:35], 2, v[170:171]
	s_waitcnt lgkmcnt(0)
	v_add_f32_e32 v68, v68, v69
	global_atomic_add_f32 v[70:71], v68, off offset:512

; __device__ __forceinline__ float bflo(unsigned w) { return __uint_as_float(w << 16); }
;     __device__ __forceinline__ void operator()(const pg8::f32x4 (&acc)[2][2][4][2], const pg8::Unit& u, int wr, int wc, int fr, int fq) const {
;     ...
;         for (int it = 0; it < 8; ++it) {
;             const int ai = it >> 2, m = it & 3;
;             const int rl = ai * 128 + wr * 64 + m * 16 + fr;
;             const size_t off = (size_t)(prow0 + rl) * DM + col0;
;             f32x4 cur[2][2];
; #pragma unroll
;             for (int bj = 0; bj < 2; ++bj) { cur[bj][0] = *(const f32x4*)(xin + off + bj * 128); cur[bj][1] = *(const f32x4*)(xin + off + bj * 128 + 4); }
;             float ss = 0.f;
; #pragma unroll
;             for (int bj = 0; bj < 2; ++bj) {
;                 f32x4 dl0 = gv[bj][0] * acc[ai][bj][m][0], dl1 = gv[bj][1] * acc[ai][bj][m][1];
;                 bf16* dp = d1 + (size_t)(u.pm * 256 + rl) * DM + col0 + bj * 128;
;                 if (dmode == 2) {
;                     const u32x4 dw = *(const u32x4*)dp;
;                     dl0 += (f32x4){bflo(dw[0]), bfhi(dw[0]), bflo(dw[1]), bfhi(dw[1])}; dl1 += (f32x4){bflo(dw[2]), bfhi(dw[2]), bflo(dw[3]), bfhi(dw[3])};
;                 }
;                 const f32x4 x0 = cur[bj][0] + dl0, x1 = cur[bj][1] + dl1;
;                 if (dmode == 1) { u32x4 dw; dw.x = cvt_pk_bf16(dl0[0], dl0[1]); dw.y = cvt_pk_bf16(dl0[2], dl0[3]); dw.z = cvt_pk_bf16(dl1[0], dl1[1]); dw.w = cvt_pk_bf16(dl1[2], dl1[3]); *(u32x4*)dp = dw; }
;                 else { *(f32x4*)(xout + off + bj * 128) = x0; *(f32x4*)(xout + off + bj * 128 + 4) = x1; }
;                 if (has_next) {
;                     ss += (x0[0] * x0[0] + x0[1] * x0[1]) + (x0[2] * x0[2] + x0[3] * x0[3]) + (x1[0] * x1[0] + x1[1] * x1[1]) + (x1[2] * x1[2] + x1[3] * x1[3]);
;                     const f32x4 y0 = x0 * gm[bj][0], y1 = x1 * gm[bj][1];
;                     u32x4 w; w.x = cvt_pk_bf16(y0[0], y0[1]); w.y = cvt_pk_bf16(y0[2], y0[3]); w.z = cvt_pk_bf16(y1[0], y1[1]); w.w = cvt_pk_bf16(y1[2], y1[3]);
;                     *(u32x4*)(xb + (size_t)(u.pm * 256 + rl) * DM + col0 + bj * 128) = w;
;                 }
;             }
;             if (has_next) {
;                 ss += __shfl_xor(ss, 16); ss += __shfl_xor(ss, 32);
;                 if (fq == 0) atomicAdd(rowss_next + u.pm * 256 + rl, ss);
;             }
;         }
.LBB0_757:
	s_nop 0
	v_add_u32_e32 v68, s6, v212
	s_waitcnt lgkmcnt(0)
	v_ashrrev_i32_e32 v69, 31, v68
	v_add_u32_e32 v78, s34, v212
	v_lshlrev_b64 v[68:69], 10, v[68:69]
	v_ashrrev_i32_e32 v79, 31, v78
	v_lshl_add_u64 v[68:69], v[68:69], 0, v[192:193]
	v_lshlrev_b64 v[78:79], 11, v[78:79]
	v_lshlrev_b64 v[76:77], 2, v[68:69]
	v_lshl_add_u64 v[80:81], s[78:79], 0, v[78:79]
	v_lshl_add_u64 v[72:73], s[74:75], 0, v[76:77]
	v_lshl_add_u64 v[80:81], v[192:193], 1, v[80:81]
	global_load_dwordx4 v[82:85], v[72:73], off offset:16
	global_load_dwordx4 v[86:89], v[72:73], off
	global_load_dwordx4 v[68:71], v[72:73], off offset:528
	s_nop 0
	global_load_dwordx4 v[72:75], v[72:73], off offset:512
	v_lshl_add_u64 v[78:79], s[86:87], 0, v[78:79]
	global_load_dwordx4 v[90:93], v[80:81], off
	global_load_dwordx4 v[240:243], v[80:81], off offset:256
	v_lshl_add_u64 v[76:77], s[58:59], 0, v[76:77]
	s_and_b64 vcc, exec, s[40:41]
	v_lshl_add_u64 v[78:79], v[192:193], 1, v[78:79]
	s_waitcnt vmcnt(0)
	v_lshlrev_b32_e32 v94, 16, v90
	v_and_b32_e32 v95, 0xffff0000, v90
	v_lshlrev_b32_e32 v90, 16, v91
	v_and_b32_e32 v91, 0xffff0000, v91
	v_pk_fma_f32 v[66:67], v[66:67], v[46:47], v[90:91]
	v_lshlrev_b32_e32 v90, 16, v92
	v_and_b32_e32 v91, 0xffff0000, v92
	v_lshlrev_b32_e32 v92, 16, v93
	v_and_b32_e32 v93, 0xffff0000, v93
	v_pk_fma_f32 v[64:65], v[64:65], v[44:45], v[94:95]
	v_pk_fma_f32 v[60:61], v[60:61], v[48:49], v[90:91]
	v_pk_fma_f32 v[62:63], v[62:63], v[50:51], v[92:93]
	v_pk_add_f32 v[66:67], v[88:89], v[66:67]
	v_pk_add_f32 v[64:65], v[86:87], v[64:65]
	v_pk_add_f32 v[62:63], v[84:85], v[62:63]
	v_pk_add_f32 v[60:61], v[82:83], v[60:61]
	v_mov_b32_e32 v82, 0
	global_store_dwordx4 v[76:77], v[64:67], off
	global_store_dwordx4 v[76:77], v[60:63], off offset:16
	s_cbranch_vccnz .LBB0_759
	v_pk_mul_f32 v[82:83], v[66:67], v[66:67]
	v_pk_mul_f32 v[84:85], v[64:65], v[64:65]
	v_pk_mul_f32 v[66:67], v[196:197], v[66:67]
	v_pk_mov_b32 v[86:87], v[84:85], v[82:83] op_sel:[1,0]
	v_mov_b32_e32 v85, v83
	v_pk_add_f32 v[82:83], v[86:87], v[84:85]
	v_pk_mul_f32 v[84:85], v[62:63], v[62:63]
	v_pk_mul_f32 v[86:87], v[60:61], v[60:61]
	v_mov_b32_e32 v88, v84
	v_mov_b32_e32 v89, v86
	v_mov_b32_e32 v86, v85
	v_pk_add_f32 v[84:85], v[88:89], v[86:87]
	v_add_f32_e32 v82, v82, v83
	v_add_f32_e32 v82, v85, v82
	v_add_f32_e32 v82, v84, v82
	v_pk_mul_f32 v[64:65], v[194:195], v[64:65]
	v_pk_mul_f32 v[84:85], v[198:199], v[62:63]
	v_pk_mul_f32 v[62:63], v[190:191], v[60:61]
	v_cvt_pk_bf16_f32 v60, v64, v65
	v_cvt_pk_bf16_f32 v61, v66, v67
	v_cvt_pk_bf16_f32 v62, v62, v63
	v_cvt_pk_bf16_f32 v63, v84, v85
	global_store_dwordx4 v[78:79], v[60:63], off
.LBB0_759:
	s_and_b64 vcc, exec, s[40:41]
	s_nop 1
	v_mov_b64_e32 v[60:61], v[240:241]
	v_mov_b64_e32 v[62:63], v[242:243]
	v_lshlrev_b32_e32 v64, 16, v60
	v_and_b32_e32 v65, 0xffff0000, v60
	v_lshlrev_b32_e32 v60, 16, v61
	v_and_b32_e32 v61, 0xffff0000, v61
	v_pk_fma_f32 v[58:59], v[58:59], v[30:31], v[60:61]
	v_lshlrev_b32_e32 v60, 16, v62
	v_and_b32_e32 v61, 0xffff0000, v62
	v_lshlrev_b32_e32 v62, 16, v63
	v_and_b32_e32 v63, 0xffff0000, v63
	v_pk_fma_f32 v[56:57], v[56:57], v[28:29], v[64:65]
	v_pk_fma_f32 v[52:53], v[52:53], v[40:41], v[60:61]
	v_pk_fma_f32 v[54:55], v[54:55], v[42:43], v[62:63]
	v_pk_add_f32 v[58:59], v[74:75], v[58:59]
	v_pk_add_f32 v[56:57], v[72:73], v[56:57]
	v_pk_add_f32 v[54:55], v[70:71], v[54:55]
	v_pk_add_f32 v[52:53], v[68:69], v[52:53]
	global_store_dwordx4 v[76:77], v[56:59], off offset:512
	global_store_dwordx4 v[76:77], v[52:55], off offset:528
	s_cbranch_vccnz .LBB0_763
	v_pk_mul_f32 v[60:61], v[188:189], v[58:59]
	v_mul_f32_e32 v64, v57, v57
	v_mul_f32_e32 v59, v59, v59
	v_mul_f32_e32 v63, v53, v53
	v_fmac_f32_e32 v64, v56, v56
	v_fmac_f32_e32 v59, v58, v58
	v_mul_f32_e32 v62, v55, v55
	v_fmac_f32_e32 v63, v52, v52
	v_add_f32_e32 v58, v64, v59
	v_fmac_f32_e32 v62, v54, v54
	v_add_f32_e32 v58, v63, v58
	v_add_f32_e32 v58, v62, v58
	v_and_b32_e32 v59, 64, v222
	v_add_f32_e32 v64, v82, v58
	v_xor_b32_e32 v58, 16, v222
	v_add_u32_e32 v65, 64, v59
	v_cmp_lt_i32_e32 vcc, v58, v65
	v_pk_mul_f32 v[62:63], v[182:183], v[52:53]
	v_xor_b32_e32 v53, 32, v222
	v_cndmask_b32_e32 v58, v222, v58, vcc
	v_lshlrev_b32_e32 v58, 2, v58
	ds_bpermute_b32 v66, v58, v64
	v_cmp_lt_i32_e32 vcc, v53, v65
	v_pk_mul_f32 v[56:57], v[184:185], v[56:57]
	v_pk_mul_f32 v[58:59], v[186:187], v[54:55]
	v_cndmask_b32_e32 v53, v222, v53, vcc
	s_waitcnt lgkmcnt(0)
	v_add_f32_e32 v52, v64, v66
	v_lshlrev_b32_e32 v53, 2, v53
	ds_bpermute_b32 v53, v53, v52
	v_cvt_pk_bf16_f32 v54, v56, v57
	v_cvt_pk_bf16_f32 v55, v60, v61
	v_cvt_pk_bf16_f32 v56, v62, v63
	v_cvt_pk_bf16_f32 v57, v58, v59
	global_store_dwordx4 v[78:79], v[54:57], off offset:256
	s_and_saveexec_b64 s[4:5], s[36:37]
	s_cbranch_execz .LBB0_762
	v_lshl_add_u64 v[54:55], s[34:35], 2, v[172:173]
	s_waitcnt lgkmcnt(0)
	v_add_f32_e32 v52, v52, v53
	global_atomic_add_f32 v[54:55], v52, off offset:512

; __device__ __forceinline__ float bflo(unsigned w) { return __uint_as_float(w << 16); }
;     __device__ __forceinline__ void operator()(const pg8::f32x4 (&acc)[2][2][4][2], const pg8::Unit& u, int wr, int wc, int fr, int fq) const {
;     ...
;         for (int it = 0; it < 8; ++it) {
;             const int ai = it >> 2, m = it & 3;
;             const int rl = ai * 128 + wr * 64 + m * 16 + fr;
;             const size_t off = (size_t)(prow0 + rl) * DM + col0;
;             f32x4 cur[2][2];
; #pragma unroll
;             for (int bj = 0; bj < 2; ++bj) { cur[bj][0] = *(const f32x4*)(xin + off + bj * 128); cur[bj][1] = *(const f32x4*)(xin + off + bj * 128 + 4); }
;             float ss = 0.f;
; #pragma unroll
;             for (int bj = 0; bj < 2; ++bj) {
;                 f32x4 dl0 = gv[bj][0] * acc[ai][bj][m][0], dl1 = gv[bj][1] * acc[ai][bj][m][1];
;                 bf16* dp = d1 + (size_t)(u.pm * 256 + rl) * DM + col0 + bj * 128;
;                 if (dmode == 2) {
;                     const u32x4 dw = *(const u32x4*)dp;
;                     dl0 += (f32x4){bflo(dw[0]), bfhi(dw[0]), bflo(dw[1]), bfhi(dw[1])}; dl1 += (f32x4){bflo(dw[2]), bfhi(dw[2]), bflo(dw[3]), bfhi(dw[3])};
;                 }
;                 const f32x4 x0 = cur[bj][0] + dl0, x1 = cur[bj][1] + dl1;
;                 if (dmode == 1) { u32x4 dw; dw.x = cvt_pk_bf16(dl0[0], dl0[1]); dw.y = cvt_pk_bf16(dl0[2], dl0[3]); dw.z = cvt_pk_bf16(dl1[0], dl1[1]); dw.w = cvt_pk_bf16(dl1[2], dl1[3]); *(u32x4*)dp = dw; }
;                 else { *(f32x4*)(xout + off + bj * 128) = x0; *(f32x4*)(xout + off + bj * 128 + 4) = x1; }
;                 if (has_next) {
;                     ss += (x0[0] * x0[0] + x0[1] * x0[1]) + (x0[2] * x0[2] + x0[3] * x0[3]) + (x1[0] * x1[0] + x1[1] * x1[1]) + (x1[2] * x1[2] + x1[3] * x1[3]);
;                     const f32x4 y0 = x0 * gm[bj][0], y1 = x1 * gm[bj][1];
;                     u32x4 w; w.x = cvt_pk_bf16(y0[0], y0[1]); w.y = cvt_pk_bf16(y0[2], y0[3]); w.z = cvt_pk_bf16(y1[0], y1[1]); w.w = cvt_pk_bf16(y1[2], y1[3]);
;                     *(u32x4*)(xb + (size_t)(u.pm * 256 + rl) * DM + col0 + bj * 128) = w;
;                 }
;             }
;             if (has_next) {
;                 ss += __shfl_xor(ss, 16); ss += __shfl_xor(ss, 32);
;                 if (fq == 0) atomicAdd(rowss_next + u.pm * 256 + rl, ss);
;             }
;         }
.LBB0_763:
	s_nop 0
	v_add_u32_e32 v52, s6, v213
	s_waitcnt lgkmcnt(0)
	v_ashrrev_i32_e32 v53, 31, v52
	v_add_u32_e32 v62, s34, v213
	v_lshlrev_b64 v[52:53], 10, v[52:53]
	v_ashrrev_i32_e32 v63, 31, v62
	v_lshl_add_u64 v[52:53], v[52:53], 0, v[192:193]
	v_lshlrev_b64 v[62:63], 11, v[62:63]
	v_lshlrev_b64 v[60:61], 2, v[52:53]
	v_lshl_add_u64 v[64:65], s[78:79], 0, v[62:63]
	v_lshl_add_u64 v[56:57], s[74:75], 0, v[60:61]
	v_lshl_add_u64 v[64:65], v[192:193], 1, v[64:65]
	global_load_dwordx4 v[66:69], v[56:57], off offset:16
	global_load_dwordx4 v[70:73], v[56:57], off
	global_load_dwordx4 v[52:55], v[56:57], off offset:528
	s_nop 0
	global_load_dwordx4 v[56:59], v[56:57], off offset:512
	v_lshl_add_u64 v[62:63], s[86:87], 0, v[62:63]
	global_load_dwordx4 v[74:77], v[64:65], off
	global_load_dwordx4 v[240:243], v[64:65], off offset:256
	v_lshl_add_u64 v[60:61], s[58:59], 0, v[60:61]
	s_and_b64 vcc, exec, s[40:41]
	v_lshl_add_u64 v[62:63], v[192:193], 1, v[62:63]
	s_waitcnt vmcnt(0)
	v_lshlrev_b32_e32 v78, 16, v74
	v_and_b32_e32 v79, 0xffff0000, v74
	v_lshlrev_b32_e32 v74, 16, v75
	v_and_b32_e32 v75, 0xffff0000, v75
	v_pk_fma_f32 v[38:39], v[38:39], v[46:47], v[74:75]
	v_lshlrev_b32_e32 v74, 16, v76
	v_and_b32_e32 v75, 0xffff0000, v76
	v_lshlrev_b32_e32 v76, 16, v77
	v_and_b32_e32 v77, 0xffff0000, v77
	v_pk_fma_f32 v[36:37], v[36:37], v[44:45], v[78:79]
	v_pk_fma_f32 v[32:33], v[32:33], v[48:49], v[74:75]
	v_pk_fma_f32 v[34:35], v[34:35], v[50:51], v[76:77]
	v_pk_add_f32 v[38:39], v[72:73], v[38:39]
	v_pk_add_f32 v[36:37], v[70:71], v[36:37]
	v_pk_add_f32 v[34:35], v[68:69], v[34:35]
	v_pk_add_f32 v[32:33], v[66:67], v[32:33]
	v_mov_b32_e32 v66, 0
	global_store_dwordx4 v[60:61], v[36:39], off
	global_store_dwordx4 v[60:61], v[32:35], off offset:16
	s_cbranch_vccnz .LBB0_765
	v_pk_mul_f32 v[66:67], v[38:39], v[38:39]
	v_pk_mul_f32 v[68:69], v[36:37], v[36:37]
	v_pk_mul_f32 v[38:39], v[196:197], v[38:39]
	v_pk_mov_b32 v[70:71], v[68:69], v[66:67] op_sel:[1,0]
	v_mov_b32_e32 v69, v67
	v_pk_add_f32 v[66:67], v[70:71], v[68:69]
	v_pk_mul_f32 v[68:69], v[34:35], v[34:35]
	v_pk_mul_f32 v[70:71], v[32:33], v[32:33]
	v_mov_b32_e32 v72, v68
	v_mov_b32_e32 v73, v70
	v_mov_b32_e32 v70, v69
	v_pk_add_f32 v[68:69], v[72:73], v[70:71]
	v_add_f32_e32 v66, v66, v67
	v_add_f32_e32 v66, v69, v66
	v_add_f32_e32 v66, v68, v66
	v_pk_mul_f32 v[36:37], v[194:195], v[36:37]
	v_pk_mul_f32 v[68:69], v[198:199], v[34:35]
	v_pk_mul_f32 v[34:35], v[190:191], v[32:33]
	v_cvt_pk_bf16_f32 v32, v36, v37
	v_cvt_pk_bf16_f32 v33, v38, v39
	v_cvt_pk_bf16_f32 v34, v34, v35
	v_cvt_pk_bf16_f32 v35, v68, v69
	global_store_dwordx4 v[62:63], v[32:35], off
.LBB0_765:
	s_and_b64 vcc, exec, s[40:41]
	s_nop 1
	v_mov_b64_e32 v[32:33], v[240:241]
	v_mov_b64_e32 v[34:35], v[242:243]
	v_lshlrev_b32_e32 v36, 16, v32
	v_and_b32_e32 v37, 0xffff0000, v32
	v_lshlrev_b32_e32 v32, 16, v33
	v_and_b32_e32 v33, 0xffff0000, v33
	v_pk_fma_f32 v[26:27], v[26:27], v[30:31], v[32:33]
	v_lshlrev_b32_e32 v32, 16, v34
	v_and_b32_e32 v33, 0xffff0000, v34
	v_lshlrev_b32_e32 v34, 16, v35
	v_and_b32_e32 v35, 0xffff0000, v35
	v_pk_fma_f32 v[24:25], v[24:25], v[28:29], v[36:37]
	v_pk_fma_f32 v[20:21], v[20:21], v[40:41], v[32:33]
	v_pk_fma_f32 v[22:23], v[22:23], v[42:43], v[34:35]
	v_pk_add_f32 v[26:27], v[58:59], v[26:27]
	v_pk_add_f32 v[24:25], v[56:57], v[24:25]
	v_pk_add_f32 v[22:23], v[54:55], v[22:23]
	v_pk_add_f32 v[20:21], v[52:53], v[20:21]
	global_store_dwordx4 v[60:61], v[24:27], off offset:512
	global_store_dwordx4 v[60:61], v[20:23], off offset:528
	s_cbranch_vccnz .LBB0_769
	v_pk_mul_f32 v[32:33], v[188:189], v[26:27]
	v_mul_f32_e32 v36, v25, v25
	v_mul_f32_e32 v27, v27, v27
	v_mul_f32_e32 v35, v21, v21
	v_fmac_f32_e32 v36, v24, v24
	v_fmac_f32_e32 v27, v26, v26
	v_mul_f32_e32 v34, v23, v23
	v_fmac_f32_e32 v35, v20, v20
	v_add_f32_e32 v26, v36, v27
	v_fmac_f32_e32 v34, v22, v22
	v_add_f32_e32 v26, v35, v26
	v_add_f32_e32 v26, v34, v26
	v_and_b32_e32 v27, 64, v222
	v_add_f32_e32 v36, v66, v26
	v_xor_b32_e32 v26, 16, v222
	v_add_u32_e32 v37, 64, v27
	v_cmp_lt_i32_e32 vcc, v26, v37
	v_pk_mul_f32 v[34:35], v[182:183], v[20:21]
	v_xor_b32_e32 v21, 32, v222
	v_cndmask_b32_e32 v26, v222, v26, vcc
	v_lshlrev_b32_e32 v26, 2, v26
	ds_bpermute_b32 v38, v26, v36
	v_cmp_lt_i32_e32 vcc, v21, v37
	v_pk_mul_f32 v[24:25], v[184:185], v[24:25]
	v_pk_mul_f32 v[26:27], v[186:187], v[22:23]
	v_cndmask_b32_e32 v21, v222, v21, vcc
	s_waitcnt lgkmcnt(0)
	v_add_f32_e32 v20, v36, v38
	v_lshlrev_b32_e32 v21, 2, v21
	ds_bpermute_b32 v21, v21, v20
	v_cvt_pk_bf16_f32 v22, v24, v25
	v_cvt_pk_bf16_f32 v23, v32, v33
	v_cvt_pk_bf16_f32 v24, v34, v35
	v_cvt_pk_bf16_f32 v25, v26, v27
	global_store_dwordx4 v[62:63], v[22:25], off offset:256
	s_and_saveexec_b64 s[4:5], s[36:37]
	s_cbranch_execz .LBB0_768
	v_lshl_add_u64 v[22:23], s[34:35], 2, v[174:175]
	s_waitcnt lgkmcnt(0)
	v_add_f32_e32 v20, v20, v21
	global_atomic_add_f32 v[22:23], v20, off offset:512

; __device__ __forceinline__ float bflo(unsigned w) { return __uint_as_float(w << 16); }
;     __device__ __forceinline__ void operator()(const pg8::f32x4 (&acc)[2][2][4][2], const pg8::Unit& u, int wr, int wc, int fr, int fq) const {
;     ...
;         for (int it = 0; it < 8; ++it) {
;             const int ai = it >> 2, m = it & 3;
;             const int rl = ai * 128 + wr * 64 + m * 16 + fr;
;             const size_t off = (size_t)(prow0 + rl) * DM + col0;
;             f32x4 cur[2][2];
; #pragma unroll
;             for (int bj = 0; bj < 2; ++bj) { cur[bj][0] = *(const f32x4*)(xin + off + bj * 128); cur[bj][1] = *(const f32x4*)(xin + off + bj * 128 + 4); }
;             float ss = 0.f;
; #pragma unroll
;             for (int bj = 0; bj < 2; ++bj) {
;                 f32x4 dl0 = gv[bj][0] * acc[ai][bj][m][0], dl1 = gv[bj][1] * acc[ai][bj][m][1];
;                 bf16* dp = d1 + (size_t)(u.pm * 256 + rl) * DM + col0 + bj * 128;
;                 if (dmode == 2) {
;                     const u32x4 dw = *(const u32x4*)dp;
;                     dl0 += (f32x4){bflo(dw[0]), bfhi(dw[0]), bflo(dw[1]), bfhi(dw[1])}; dl1 += (f32x4){bflo(dw[2]), bfhi(dw[2]), bflo(dw[3]), bfhi(dw[3])};
;                 }
;                 const f32x4 x0 = cur[bj][0] + dl0, x1 = cur[bj][1] + dl1;
;                 if (dmode == 1) { u32x4 dw; dw.x = cvt_pk_bf16(dl0[0], dl0[1]); dw.y = cvt_pk_bf16(dl0[2], dl0[3]); dw.z = cvt_pk_bf16(dl1[0], dl1[1]); dw.w = cvt_pk_bf16(dl1[2], dl1[3]); *(u32x4*)dp = dw; }
;                 else { *(f32x4*)(xout + off + bj * 128) = x0; *(f32x4*)(xout + off + bj * 128 + 4) = x1; }
;                 if (has_next) {
;                     ss += (x0[0] * x0[0] + x0[1] * x0[1]) + (x0[2] * x0[2] + x0[3] * x0[3]) + (x1[0] * x1[0] + x1[1] * x1[1]) + (x1[2] * x1[2] + x1[3] * x1[3]);
;                     const f32x4 y0 = x0 * gm[bj][0], y1 = x1 * gm[bj][1];
;                     u32x4 w; w.x = cvt_pk_bf16(y0[0], y0[1]); w.y = cvt_pk_bf16(y0[2], y0[3]); w.z = cvt_pk_bf16(y1[0], y1[1]); w.w = cvt_pk_bf16(y1[2], y1[3]);
;                     *(u32x4*)(xb + (size_t)(u.pm * 256 + rl) * DM + col0 + bj * 128) = w;
;                 }
;             }
;             if (has_next) {
;                 ss += __shfl_xor(ss, 16); ss += __shfl_xor(ss, 32);
;                 if (fq == 0) atomicAdd(rowss_next + u.pm * 256 + rl, ss);
;             }
;         }
.LBB0_769:
	s_nop 0
	v_add_u32_e32 v20, s6, v214
	s_waitcnt lgkmcnt(0)
	v_ashrrev_i32_e32 v21, 31, v20
	v_add_u32_e32 v34, s34, v214
	v_lshlrev_b64 v[20:21], 10, v[20:21]
	v_ashrrev_i32_e32 v35, 31, v34
	v_lshl_add_u64 v[20:21], v[20:21], 0, v[192:193]
	v_lshlrev_b64 v[34:35], 11, v[34:35]
	v_lshlrev_b64 v[32:33], 2, v[20:21]
	v_lshl_add_u64 v[36:37], s[78:79], 0, v[34:35]
	v_lshl_add_u64 v[24:25], s[74:75], 0, v[32:33]
	v_lshl_add_u64 v[36:37], v[192:193], 1, v[36:37]
	global_load_dwordx4 v[52:55], v[24:25], off offset:16
	global_load_dwordx4 v[56:59], v[24:25], off
	global_load_dwordx4 v[20:23], v[24:25], off offset:528
	s_nop 0
	global_load_dwordx4 v[24:27], v[24:25], off offset:512
	v_lshl_add_u64 v[34:35], s[86:87], 0, v[34:35]
	global_load_dwordx4 v[60:63], v[36:37], off
	global_load_dwordx4 v[240:243], v[36:37], off offset:256
	v_lshl_add_u64 v[32:33], s[58:59], 0, v[32:33]
	s_and_b64 vcc, exec, s[40:41]
	v_lshl_add_u64 v[34:35], v[192:193], 1, v[34:35]
	s_waitcnt vmcnt(0)
	v_lshlrev_b32_e32 v38, 16, v60
	v_and_b32_e32 v39, 0xffff0000, v60
	v_lshlrev_b32_e32 v60, 16, v61
	v_and_b32_e32 v61, 0xffff0000, v61
	v_pk_fma_f32 v[16:17], v[16:17], v[44:45], v[38:39]
	v_lshlrev_b32_e32 v38, 16, v62
	v_and_b32_e32 v39, 0xffff0000, v62
	v_lshlrev_b32_e32 v44, 16, v63
	v_and_b32_e32 v45, 0xffff0000, v63
	v_pk_fma_f32 v[18:19], v[18:19], v[46:47], v[60:61]
	v_pk_fma_f32 v[12:13], v[12:13], v[48:49], v[38:39]
	v_pk_fma_f32 v[14:15], v[14:15], v[50:51], v[44:45]
	v_pk_add_f32 v[18:19], v[58:59], v[18:19]
	v_pk_add_f32 v[16:17], v[56:57], v[16:17]
	v_pk_add_f32 v[14:15], v[54:55], v[14:15]
	v_pk_add_f32 v[12:13], v[52:53], v[12:13]
	v_mov_b32_e32 v38, 0
	global_store_dwordx4 v[32:33], v[16:19], off
	global_store_dwordx4 v[32:33], v[12:15], off offset:16
	s_cbranch_vccnz .LBB0_771
	v_pk_mul_f32 v[38:39], v[18:19], v[18:19]
	v_pk_mul_f32 v[44:45], v[16:17], v[16:17]
	v_pk_mul_f32 v[18:19], v[196:197], v[18:19]
	v_pk_mov_b32 v[46:47], v[44:45], v[38:39] op_sel:[1,0]
	v_mov_b32_e32 v45, v39
	v_pk_add_f32 v[38:39], v[46:47], v[44:45]
	v_pk_mul_f32 v[44:45], v[14:15], v[14:15]
	v_pk_mul_f32 v[46:47], v[12:13], v[12:13]
	v_mov_b32_e32 v48, v44
	v_mov_b32_e32 v49, v46
	v_mov_b32_e32 v46, v45
	v_pk_add_f32 v[44:45], v[48:49], v[46:47]
	v_add_f32_e32 v38, v38, v39
	v_add_f32_e32 v38, v45, v38
	v_add_f32_e32 v38, v44, v38
	v_pk_mul_f32 v[16:17], v[194:195], v[16:17]
	v_pk_mul_f32 v[44:45], v[198:199], v[14:15]
	v_pk_mul_f32 v[14:15], v[190:191], v[12:13]
	v_cvt_pk_bf16_f32 v12, v16, v17
	v_cvt_pk_bf16_f32 v13, v18, v19
	v_cvt_pk_bf16_f32 v14, v14, v15
	v_cvt_pk_bf16_f32 v15, v44, v45
	global_store_dwordx4 v[34:35], v[12:15], off
.LBB0_771:
	v_readlane_b32 s74, v254, 33
	s_and_b64 vcc, exec, s[40:41]
	v_readlane_b32 s75, v254, 34
	s_nop 1
	v_mov_b64_e32 v[12:13], v[240:241]
	v_mov_b64_e32 v[14:15], v[242:243]
	v_lshlrev_b32_e32 v16, 16, v12
	v_and_b32_e32 v17, 0xffff0000, v12
	v_lshlrev_b32_e32 v12, 16, v13
	v_and_b32_e32 v13, 0xffff0000, v13
	v_pk_fma_f32 v[10:11], v[10:11], v[30:31], v[12:13]
	v_lshlrev_b32_e32 v12, 16, v14
	v_and_b32_e32 v13, 0xffff0000, v14
	v_lshlrev_b32_e32 v14, 16, v15
	v_and_b32_e32 v15, 0xffff0000, v15
	v_pk_fma_f32 v[8:9], v[8:9], v[28:29], v[16:17]
	v_pk_fma_f32 v[4:5], v[4:5], v[40:41], v[12:13]
	v_pk_fma_f32 v[6:7], v[6:7], v[42:43], v[14:15]
	v_pk_add_f32 v[10:11], v[26:27], v[10:11]
	v_pk_add_f32 v[8:9], v[24:25], v[8:9]
	v_pk_add_f32 v[6:7], v[22:23], v[6:7]
	v_pk_add_f32 v[4:5], v[20:21], v[4:5]
	global_store_dwordx4 v[32:33], v[8:11], off offset:512
	global_store_dwordx4 v[32:33], v[4:7], off offset:528
	s_cbranch_vccnz .LBB0_775
	v_pk_mul_f32 v[12:13], v[188:189], v[10:11]
	v_mul_f32_e32 v16, v9, v9
	v_mul_f32_e32 v11, v11, v11
	v_mul_f32_e32 v15, v5, v5
	v_fmac_f32_e32 v16, v8, v8
	v_fmac_f32_e32 v11, v10, v10
	v_mul_f32_e32 v14, v7, v7
	v_fmac_f32_e32 v15, v4, v4
	v_add_f32_e32 v10, v16, v11
	v_fmac_f32_e32 v14, v6, v6
	v_add_f32_e32 v10, v15, v10
	v_add_f32_e32 v10, v14, v10
	v_and_b32_e32 v11, 64, v222
	v_add_f32_e32 v16, v38, v10
	v_xor_b32_e32 v10, 16, v222
	v_add_u32_e32 v17, 64, v11
	v_cmp_lt_i32_e32 vcc, v10, v17
	v_pk_mul_f32 v[14:15], v[182:183], v[4:5]
	v_xor_b32_e32 v5, 32, v222
	v_cndmask_b32_e32 v10, v222, v10, vcc
	v_lshlrev_b32_e32 v10, 2, v10
	ds_bpermute_b32 v18, v10, v16
	v_cmp_lt_i32_e32 vcc, v5, v17
	v_pk_mul_f32 v[8:9], v[184:185], v[8:9]
	v_pk_mul_f32 v[10:11], v[186:187], v[6:7]
	v_cndmask_b32_e32 v5, v222, v5, vcc
	s_waitcnt lgkmcnt(0)
	v_add_f32_e32 v4, v16, v18
	v_lshlrev_b32_e32 v5, 2, v5
	ds_bpermute_b32 v5, v5, v4
	v_cvt_pk_bf16_f32 v6, v8, v9
	v_cvt_pk_bf16_f32 v7, v12, v13
	v_cvt_pk_bf16_f32 v8, v14, v15
	v_cvt_pk_bf16_f32 v9, v10, v11
	global_store_dwordx4 v[34:35], v[6:9], off offset:256
	s_and_saveexec_b64 s[4:5], s[36:37]
	s_cbranch_execz .LBB0_774
	v_lshl_add_u64 v[6:7], s[34:35], 2, v[176:177]
	s_waitcnt lgkmcnt(0)
	v_add_f32_e32 v4, v4, v5
	global_atomic_add_f32 v[6:7], v4, off offset:512
